# r43 + gdn_pre per-chunk epilogue: 18 LDS reads hoisted/pipelined across the 6 convert+store sections with counted lgkm waits
# baseline (speedup 1.0000x reference)
.LBB0_293:
	s_or_b64 exec, exec, s[2:3]
	s_barrier
	s_nop 14
	ds_write2_b32 v145, v2, v3 offset1:132
	v_add_u32_e32 v2, 0x400, v145
	ds_write2_b32 v2, v4, v5 offset0:8 offset1:140
	v_add_u32_e32 v2, 0x1000, v145
	ds_write2_b32 v2, v6, v7 offset0:32 offset1:164
	v_add_u32_e32 v2, 0x1400, v145
	ds_write2_b32 v2, v8, v9 offset0:40 offset1:172
	v_add_u32_e32 v2, 0x2000, v145
	ds_write2_b32 v2, v10, v11 offset0:64 offset1:196
	v_add_u32_e32 v2, 0x2400, v145
	ds_write2_b32 v2, v12, v13 offset0:72 offset1:204
	v_add_u32_e32 v2, 0x3000, v145
	v_readlane_b32 s40, v253, 32
	ds_write2_b32 v2, v14, v15 offset0:96 offset1:228
	v_add_u32_e32 v2, 0x3400, v145
	v_readlane_b32 s40, v253, 14
	ds_write2_b32 v2, v16, v17 offset0:104 offset1:236
	s_waitcnt lgkmcnt(0)
	v_mov_b32_e32 v2, s40
	s_barrier
	ds_read_b32 v16, v2
	ds_read_b128 v[198:201], v77 offset:256
	ds_read_b128 v[202:205], v77 offset:272
	ds_read_b128 v[206:209], v78
	ds_read_b128 v[210:213], v78 offset:16
	ds_read_b32 v214, v79
	ds_read_b128 v[216:219], v78 offset:52224
	ds_read_b128 v[220:223], v78 offset:52240
	v_add_u32_e32 v248, 0x4400, v146
	ds_read2_b32 v[224:225], v248 offset1:68
	ds_read_b128 v[226:229], v137
	ds_read2_b32 v[230:231], v248 offset0:136 offset1:204
	s_add_u32 s2, s74, s90
	s_addc_u32 s3, 0, 0
	s_mul_i32 s38, s3, 0xa000
	s_mul_hi_u32 s39, s2, 0xa000
	s_waitcnt lgkmcnt(9)
	v_xor_b32_e32 v3, 0x80000000, v199
	v_xor_b32_e32 v2, 0x80000000, v198
	s_add_i32 s39, s39, s38
	s_mul_i32 s38, s2, 0xa000
	v_readlane_b32 s54, v253, 46
	v_cvt_pk_bf16_f32 v10, v2, v3
	v_xor_b32_e32 v2, 0x80000000, v200
	v_xor_b32_e32 v3, 0x80000000, v201
	v_readlane_b32 s55, v253, 47
	s_add_u32 s38, s54, s38
	v_cvt_pk_bf16_f32 v11, v2, v3
	s_waitcnt lgkmcnt(8)
	v_xor_b32_e32 v2, 0x80000000, v203
	v_xor_b32_e32 v3, 0x80000000, v202
	s_addc_u32 s39, s55, s39
	v_cvt_pk_bf16_f32 v12, v3, v2
	v_xor_b32_e32 v2, 0x80000000, v204
	v_xor_b32_e32 v3, 0x80000000, v205
	v_cvt_pk_bf16_f32 v13, v2, v3
	v_lshl_add_u64 v[2:3], v[40:41], 1, s[38:39]
	v_mov_b32_e32 v59, v0
	v_lshl_add_u64 v[2:3], v[2:3], 0, v[58:59]
	global_store_dwordx4 v[2:3], v[10:13], off
	v_add_u32_e32 v249, 0x4800, v146
	ds_read2_b32 v[232:233], v249 offset0:16 offset1:84
	ds_read_b128 v[234:237], v138
	ds_read2_b32 v[238:239], v249 offset0:152 offset1:220
	s_movk_i32 s38, 0x4000
	s_lshl_b64 s[2:3], s[2:3], 2
	s_add_u32 s2, s92, s2
	s_waitcnt lgkmcnt(8)
	v_pk_mul_f32 v[4:5], v[206:207], v[214:215] op_sel_hi:[1,0]
	v_pk_mul_f32 v[6:7], v[208:209], v[214:215] op_sel_hi:[1,0]
	v_cvt_pk_bf16_f32 v4, v4, v5
	v_cvt_pk_bf16_f32 v5, v6, v7
	v_pk_mul_f32 v[6:7], v[210:211], v[214:215] op_sel_hi:[1,0]
	v_pk_mul_f32 v[8:9], v[212:213], v[214:215] op_sel_hi:[1,0]
	v_cvt_pk_bf16_f32 v6, v6, v7
	v_cvt_pk_bf16_f32 v7, v8, v9
	v_add_co_u32_e32 v8, vcc, s97, v2
	s_addc_u32 s3, s93, s3
	s_nop 0
	v_addc_co_u32_e32 v9, vcc, 0, v3, vcc
	global_store_dwordx4 v[8:9], v[4:7], off
	v_add_u32_e32 v248, 0x400, v80
	v_add_u32_e32 v249, 0x800, v80
	v_add_u32_e32 v250, 0xc00, v80
	ds_read2_b32 v[240:241], v80 offset1:132
	ds_read2_b32 v[242:243], v248 offset0:8 offset1:140
	ds_read2_b32 v[244:245], v249 offset0:16 offset1:148
	ds_read2_b32 v[246:247], v250 offset0:24 offset1:156
	s_add_i32 s78, s78, 1
	s_cmp_eq_u32 s78, 4
	v_readlane_b32 s41, v253, 33
	s_waitcnt lgkmcnt(11)
	v_cvt_pk_bf16_f32 v10, v216, v217
	v_cvt_pk_bf16_f32 v11, v218, v219
	s_waitcnt lgkmcnt(10)
	v_cvt_pk_bf16_f32 v12, v220, v221
	v_add_co_u32_e32 v8, vcc, s38, v2
	v_cvt_pk_bf16_f32 v13, v222, v223
	s_nop 0
	v_addc_co_u32_e32 v9, vcc, 0, v3, vcc
	global_store_dwordx4 v[8:9], v[10:13], off
	s_movk_i32 s38, 0x6000
	v_readlane_b32 s42, v253, 34
	v_readlane_b32 s43, v253, 35
	v_readlane_b32 s44, v253, 36
	s_waitcnt lgkmcnt(8)
	v_sub_f32_e32 v4, v16, v226
	v_sub_f32_e32 v5, v16, v227
	v_mul_f32_e32 v4, 0x3fb8aa3b, v4
	v_mul_f32_e32 v5, 0x3fb8aa3b, v5
	v_exp_f32_e32 v4, v4
	v_exp_f32_e32 v5, v5
	v_sub_f32_e32 v6, v16, v228
	v_sub_f32_e32 v7, v16, v229
	v_mul_f32_e32 v6, 0x3fb8aa3b, v6
	v_pk_mul_f32 v[224:225], v[224:225], v[4:5]
	v_mul_f32_e32 v7, 0x3fb8aa3b, v7
	v_exp_f32_e32 v6, v6
	v_exp_f32_e32 v7, v7
	v_readlane_b32 s45, v253, 37
	v_readlane_b32 s46, v253, 38
	v_readlane_b32 s47, v253, 39
	s_waitcnt lgkmcnt(7)
	v_pk_mul_f32 v[230:231], v[230:231], v[6:7]
	v_readlane_b32 s48, v253, 40
	v_readlane_b32 s49, v253, 41
	v_readlane_b32 s50, v253, 42
	v_readlane_b32 s51, v253, 43
	s_waitcnt lgkmcnt(5)
	v_sub_f32_e32 v4, v16, v234
	v_sub_f32_e32 v5, v16, v235
	v_mul_f32_e32 v4, 0x3fb8aa3b, v4
	v_mul_f32_e32 v5, 0x3fb8aa3b, v5
	v_exp_f32_e32 v4, v4
	v_exp_f32_e32 v5, v5
	v_sub_f32_e32 v6, v16, v236
	v_sub_f32_e32 v7, v16, v237
	v_mul_f32_e32 v6, 0x3fb8aa3b, v6
	v_pk_mul_f32 v[232:233], v[232:233], v[4:5]
	v_mul_f32_e32 v7, 0x3fb8aa3b, v7
	v_exp_f32_e32 v6, v6
	v_exp_f32_e32 v7, v7
	v_readlane_b32 s52, v253, 44
	v_readlane_b32 s53, v253, 45
	s_waitcnt lgkmcnt(4)
	v_pk_mul_f32 v[14:15], v[238:239], v[6:7]
	v_cvt_pk_bf16_f32 v4, v224, v225
	v_add_co_u32_e32 v8, vcc, s38, v2
	v_cvt_pk_bf16_f32 v5, v230, v231
	v_cvt_pk_bf16_f32 v6, v232, v233
	v_cvt_pk_bf16_f32 v7, v14, v15
	v_addc_co_u32_e32 v9, vcc, 0, v3, vcc
	global_store_dwordx4 v[8:9], v[4:7], off
	s_mov_b32 s38, 0x8000
	v_add_co_u32_e32 v2, vcc, s38, v2
	s_waitcnt lgkmcnt(3)
	v_cvt_pk_bf16_f32 v10, v240, v241
	s_waitcnt lgkmcnt(2)
	v_cvt_pk_bf16_f32 v11, v242, v243
	s_waitcnt lgkmcnt(1)
	v_cvt_pk_bf16_f32 v12, v244, v245
	s_waitcnt lgkmcnt(0)
	v_cvt_pk_bf16_f32 v13, v246, v247
	v_addc_co_u32_e32 v3, vcc, 0, v3, vcc
	global_store_dwordx4 v[2:3], v[10:13], off
	v_mul_f32_e32 v2, 0x3fb8aa3b, v16
	v_exp_f32_e32 v2, v2
	global_store_dword v0, v2, s[2:3]
	s_barrier
	s_cbranch_scc1 .LBB0_477
